# gate/mix phase-4 epilogue stores widened in place; in-proj epilogue quads built directly by the bf16 converts (no copies)
# speedup vs baseline: 1.0488x; 1.0033x over previous
; DEVI void phase4(const Params& p, int l, char* lds, float* p4s) {
;     ...
; #pragma unroll
;     for (int ni = 0; ni < 4; ++ni)
; #pragma unroll
;       for (int mi = 0; mi < 4; ++mi) {
;         int n = n0 + wn * 64 + ni * 16 + fq * 4;
;         int m = m0 + wm * 64 + mi * 16 + fr;
;         *(uint2*)(mixed + (long)m * LDX + n) = mixp[ni][mi];
;       }
.LBB0_403:
	v_or_b32_e32 v2, s60, v183
	v_ashrrev_i32_e32 v3, 31, v2
	v_add_u32_e32 v0, s61, v234
	v_lshl_add_u64 v[2:3], v[2:3], 1, s[96:97]
	v_mad_i64_i32 v[4:5], s[36:37], v0, s95, v[2:3]
	v_or_b32_e32 v6, 16, v0
	v_or_b32_e32 v8, 32, v0
	v_or_b32_e32 v0, 48, v0
	v_mad_i64_i32 v[6:7], s[36:37], v6, s95, v[2:3]
	v_mad_i64_i32 v[8:9], s[36:37], v8, s95, v[2:3]
	v_mad_i64_i32 v[2:3], s[36:37], v0, s95, v[2:3]
	s_and_b64 vcc, exec, s[4:5]
	s_mov_b32 s29, s27
	s_mov_b32 s20, s59
	s_mov_b32 s23, s58
	s_movk_i32 s72, 0x1800
	v_lshl_add_u64 v[4:5], v[4:5], 0, v[254:255]
	v_lshl_add_u64 v[6:7], v[6:7], 0, v[254:255]
	v_lshl_add_u64 v[8:9], v[8:9], 0, v[254:255]
	v_lshl_add_u64 v[2:3], v[2:3], 0, v[254:255]
	v_mov_b32_e32 v216, v206
	v_mov_b32_e32 v217, v207
	s_nop 1
	v_permlane16_swap_b32_e32 v214, v216
	v_permlane16_swap_b32_e32 v215, v217
	s_nop 1
	global_store_dwordx4 v[4:5], v[214:217], off
	s_nop 1
	v_mov_b32_e32 v214, v204
	v_mov_b32_e32 v215, v205
	s_nop 1
	v_permlane16_swap_b32_e32 v212, v214
	v_permlane16_swap_b32_e32 v213, v215
	s_nop 1
	global_store_dwordx4 v[6:7], v[212:215], off
	s_nop 1
	v_mov_b32_e32 v212, v202
	v_mov_b32_e32 v213, v203
	s_nop 1
	v_permlane16_swap_b32_e32 v210, v212
	v_permlane16_swap_b32_e32 v211, v213
	s_nop 1
	global_store_dwordx4 v[8:9], v[210:213], off
	s_nop 1
	v_mov_b32_e32 v210, v200
	v_mov_b32_e32 v211, v201
	s_nop 1
	v_permlane16_swap_b32_e32 v208, v210
	v_permlane16_swap_b32_e32 v209, v211
	s_nop 1
	global_store_dwordx4 v[2:3], v[208:211], off
	s_nop 1
	v_mov_b32_e32 v200, v190
	v_mov_b32_e32 v201, v191
	s_nop 1
	v_permlane16_swap_b32_e32 v198, v200
	v_permlane16_swap_b32_e32 v199, v201
	s_nop 1
	global_store_dwordx4 v[4:5], v[198:201], off offset:64
	s_nop 1
	v_mov_b32_e32 v198, v188
	v_mov_b32_e32 v199, v189
	s_nop 1
	v_permlane16_swap_b32_e32 v196, v198
	v_permlane16_swap_b32_e32 v197, v199
	s_nop 1
	global_store_dwordx4 v[6:7], v[196:199], off offset:64
	s_nop 1
	v_mov_b32_e32 v196, v186
	v_mov_b32_e32 v197, v187
	s_nop 1
	v_permlane16_swap_b32_e32 v194, v196
	v_permlane16_swap_b32_e32 v195, v197
	s_nop 1
	global_store_dwordx4 v[8:9], v[194:197], off offset:64
	s_nop 1
	v_mov_b32_e32 v194, v184
	v_mov_b32_e32 v195, v185
	s_nop 1
	v_permlane16_swap_b32_e32 v192, v194
	v_permlane16_swap_b32_e32 v193, v195
	s_nop 1
	global_store_dwordx4 v[2:3], v[192:195], off offset:64
	s_nop 1
	s_cbranch_vccnz .LBB0_473

; DEVI void phase2(const Params& p, int l, char* lds) {
;     ...
; #pragma unroll
;     for (int ni = 0; ni < 4; ++ni)
; #pragma unroll
;       for (int mi = 0; mi < 8; ++mi) {
;         f32x4 v = acc[ni][mi];
;         if (do_gelu) { v[0] = gelu_f(v[0]); v[1] = gelu_f(v[1]); v[2] = gelu_f(v[2]); v[3] = gelu_f(v[3]); }
;         int n = n0 + wn * 64 + ni * 16 + fq * 4;
;         int m = m0 + wm * 128 + mi * 16 + fr;
;         store_bf4(proj + (long)m * LDP + n, v);
;       }
.LBB0_675:
	v_cvt_pk_bf16_f32 v240, v8, v9
	v_cvt_pk_bf16_f32 v241, v6, v7
	s_and_b64 vcc, exec, s[42:43]
	s_mov_b32 s20, s47
	s_mov_b32 s23, s49
	s_mov_b32 s52, s48
	s_nop 1
	v_permlane16_swap_b32_e32 v238, v240
	v_permlane16_swap_b32_e32 v239, v241
	s_nop 1
	global_store_dwordx4 v[2:3], v[238:241], off offset:64
	s_cbranch_vccnz .LBB0_775

; DEVI float gelu_f(float x) {
;   float u = 0.7978845608028654f * (x + 0.044715f * x * x * x);
;   return x * __builtin_amdgcn_rcpf(1.f + __expf(-2.f * u));
; }
; DEVI void phase2(const Params& p, int l, char* lds) {
;     ...
; #pragma unroll
;     for (int ni = 0; ni < 4; ++ni)
; #pragma unroll
;       for (int mi = 0; mi < 8; ++mi) {
;         f32x4 v = acc[ni][mi];
;         if (do_gelu) { v[0] = gelu_f(v[0]); v[1] = gelu_f(v[1]); v[2] = gelu_f(v[2]); v[3] = gelu_f(v[3]); }
;         int n = n0 + wn * 64 + ni * 16 + fq * 4;
;         int m = m0 + wm * 128 + mi * 16 + fr;
;         store_bf4(proj + (long)m * LDP + n, v);
;       }
.LBB0_695:
	v_or_b32_e32 v2, s53, v183
	v_ashrrev_i32_e32 v3, 31, v2
	v_add_u32_e32 v138, s51, v186
	v_lshl_add_u64 v[2:3], v[2:3], 1, s[6:7]
	v_cndmask_b32_e64 v130, 0, 1, s[36:37]
	v_mad_i64_i32 v[132:133], s[28:29], v138, s72, v[2:3]
	v_cvt_pk_bf16_f32 v196, v136, v137
	v_cvt_pk_bf16_f32 v197, v134, v135
	v_cmp_ne_u32_e64 s[40:41], 1, v130
	s_andn2_b64 vcc, exec, s[36:37]
	s_cbranch_vccnz .LBB0_697
	v_mul_f32_e32 v4, 0x3d372713, v128
	v_mul_f32_e32 v5, 0x3d372713, v129
	v_mul_f32_e32 v130, 0x3d372713, v126
	v_mul_f32_e32 v131, 0x3d372713, v127
	v_mul_f32_e32 v4, v128, v4
	v_mul_f32_e32 v5, v129, v5
	v_mul_f32_e32 v130, v126, v130
	v_mul_f32_e32 v131, v127, v131
	v_fma_f32 v4, v128, v4, v128
	v_fma_f32 v5, v129, v5, v129
	v_fma_f32 v130, v126, v130, v126
	v_fma_f32 v131, v127, v131, v127
	v_mul_f32_e32 v4, 0x3f4c422a, v4
	v_mul_f32_e32 v5, 0x3f4c422a, v5
	v_mul_f32_e32 v130, 0x3f4c422a, v130
	v_mul_f32_e32 v131, 0x3f4c422a, v131
	v_mul_f32_e32 v4, -2.0, v4
	v_mul_f32_e32 v5, -2.0, v5
	v_mul_f32_e32 v130, -2.0, v130
	v_mul_f32_e32 v131, -2.0, v131
	v_mul_f32_e32 v4, 0x3fb8aa3b, v4
	v_mul_f32_e32 v5, 0x3fb8aa3b, v5
	v_mul_f32_e32 v130, 0x3fb8aa3b, v130
	v_mul_f32_e32 v131, 0x3fb8aa3b, v131
	v_exp_f32_e32 v4, v4
	v_exp_f32_e32 v5, v5
	v_exp_f32_e32 v130, v130
	v_exp_f32_e32 v131, v131
	v_add_f32_e32 v4, 1.0, v4
	v_add_f32_e32 v5, 1.0, v5
	v_add_f32_e32 v130, 1.0, v130
	v_add_f32_e32 v131, 1.0, v131
	v_rcp_f32_e32 v4, v4
	v_rcp_f32_e32 v130, v130
	v_rcp_f32_e32 v131, v131
	v_rcp_f32_e32 v5, v5
	v_pk_mul_f32 v[126:127], v[126:127], v[130:131]
	v_pk_mul_f32 v[128:129], v[128:129], v[4:5]
.LBB0_697:
	v_or_b32_e32 v4, 16, v138
	v_mad_i64_i32 v[130:131], s[28:29], v4, s72, v[2:3]
	v_cvt_pk_bf16_f32 v200, v128, v129
	v_cvt_pk_bf16_f32 v201, v126, v127
	s_and_b64 vcc, exec, s[40:41]
	s_cbranch_vccnz .LBB0_699
	v_mul_f32_e32 v4, 0x3d372713, v124
	v_mul_f32_e32 v5, 0x3d372713, v125
	v_mul_f32_e32 v126, 0x3d372713, v122
	v_mul_f32_e32 v127, 0x3d372713, v123
	v_mul_f32_e32 v4, v124, v4
	v_mul_f32_e32 v5, v125, v5
	v_mul_f32_e32 v126, v122, v126
	v_mul_f32_e32 v127, v123, v127
	v_fma_f32 v4, v124, v4, v124
	v_fma_f32 v5, v125, v5, v125
	v_fma_f32 v126, v122, v126, v122
	v_fma_f32 v127, v123, v127, v123
	v_mul_f32_e32 v4, 0x3f4c422a, v4
	v_mul_f32_e32 v5, 0x3f4c422a, v5
	v_mul_f32_e32 v126, 0x3f4c422a, v126
	v_mul_f32_e32 v127, 0x3f4c422a, v127
	v_mul_f32_e32 v4, -2.0, v4
	v_mul_f32_e32 v5, -2.0, v5
	v_mul_f32_e32 v126, -2.0, v126
	v_mul_f32_e32 v127, -2.0, v127
	v_mul_f32_e32 v4, 0x3fb8aa3b, v4
	v_mul_f32_e32 v5, 0x3fb8aa3b, v5
	v_mul_f32_e32 v126, 0x3fb8aa3b, v126
	v_mul_f32_e32 v127, 0x3fb8aa3b, v127
	v_exp_f32_e32 v4, v4
	v_exp_f32_e32 v5, v5
	v_exp_f32_e32 v126, v126
	v_exp_f32_e32 v127, v127
	v_add_f32_e32 v4, 1.0, v4
	v_add_f32_e32 v5, 1.0, v5
	v_add_f32_e32 v126, 1.0, v126
	v_add_f32_e32 v127, 1.0, v127
	v_rcp_f32_e32 v4, v4
	v_rcp_f32_e32 v126, v126
	v_rcp_f32_e32 v127, v127
	v_rcp_f32_e32 v5, v5
	v_pk_mul_f32 v[122:123], v[122:123], v[126:127]
	v_pk_mul_f32 v[124:125], v[124:125], v[4:5]
.LBB0_699:
	v_or_b32_e32 v4, 32, v138
	v_mad_i64_i32 v[126:127], s[28:29], v4, s72, v[2:3]
	v_cvt_pk_bf16_f32 v204, v124, v125
	v_cvt_pk_bf16_f32 v205, v122, v123
	s_and_b64 vcc, exec, s[40:41]
	s_cbranch_vccnz .LBB0_701
	v_mul_f32_e32 v4, 0x3d372713, v120
	v_mul_f32_e32 v5, 0x3d372713, v121
	v_mul_f32_e32 v122, 0x3d372713, v118
	v_mul_f32_e32 v123, 0x3d372713, v119
	v_mul_f32_e32 v4, v120, v4
	v_mul_f32_e32 v5, v121, v5
	v_mul_f32_e32 v122, v118, v122
	v_mul_f32_e32 v123, v119, v123
	v_fma_f32 v4, v120, v4, v120
	v_fma_f32 v5, v121, v5, v121
	v_fma_f32 v122, v118, v122, v118
	v_fma_f32 v123, v119, v123, v119
	v_mul_f32_e32 v4, 0x3f4c422a, v4
	v_mul_f32_e32 v5, 0x3f4c422a, v5
	v_mul_f32_e32 v122, 0x3f4c422a, v122
	v_mul_f32_e32 v123, 0x3f4c422a, v123
	v_mul_f32_e32 v4, -2.0, v4
	v_mul_f32_e32 v5, -2.0, v5
	v_mul_f32_e32 v122, -2.0, v122
	v_mul_f32_e32 v123, -2.0, v123
	v_mul_f32_e32 v4, 0x3fb8aa3b, v4
	v_mul_f32_e32 v5, 0x3fb8aa3b, v5
	v_mul_f32_e32 v122, 0x3fb8aa3b, v122
	v_mul_f32_e32 v123, 0x3fb8aa3b, v123
	v_exp_f32_e32 v4, v4
	v_exp_f32_e32 v5, v5
	v_exp_f32_e32 v122, v122
	v_exp_f32_e32 v123, v123
	v_add_f32_e32 v4, 1.0, v4
	v_add_f32_e32 v5, 1.0, v5
	v_add_f32_e32 v122, 1.0, v122
	v_add_f32_e32 v123, 1.0, v123
	v_rcp_f32_e32 v4, v4
	v_rcp_f32_e32 v122, v122
	v_rcp_f32_e32 v123, v123
	v_rcp_f32_e32 v5, v5
	v_pk_mul_f32 v[118:119], v[118:119], v[122:123]
	v_pk_mul_f32 v[120:121], v[120:121], v[4:5]
.LBB0_701:
	v_or_b32_e32 v4, 48, v138
	v_mad_i64_i32 v[122:123], s[28:29], v4, s72, v[2:3]
	v_cvt_pk_bf16_f32 v208, v120, v121
	v_cvt_pk_bf16_f32 v209, v118, v119
	s_and_b64 vcc, exec, s[40:41]
	s_cbranch_vccnz .LBB0_703
	v_mul_f32_e32 v4, 0x3d372713, v116
	v_mul_f32_e32 v5, 0x3d372713, v117
	v_mul_f32_e32 v118, 0x3d372713, v112
	v_mul_f32_e32 v119, 0x3d372713, v113
	v_mul_f32_e32 v4, v116, v4
	v_mul_f32_e32 v5, v117, v5
	v_mul_f32_e32 v118, v112, v118
	v_mul_f32_e32 v119, v113, v119
	v_fma_f32 v4, v116, v4, v116
	v_fma_f32 v5, v117, v5, v117
	v_fma_f32 v118, v112, v118, v112
	v_fma_f32 v119, v113, v119, v113
	v_mul_f32_e32 v4, 0x3f4c422a, v4
	v_mul_f32_e32 v5, 0x3f4c422a, v5
	v_mul_f32_e32 v118, 0x3f4c422a, v118
	v_mul_f32_e32 v119, 0x3f4c422a, v119
	v_mul_f32_e32 v4, -2.0, v4
	v_mul_f32_e32 v5, -2.0, v5
	v_mul_f32_e32 v118, -2.0, v118
	v_mul_f32_e32 v119, -2.0, v119
	v_mul_f32_e32 v4, 0x3fb8aa3b, v4
	v_mul_f32_e32 v5, 0x3fb8aa3b, v5
	v_mul_f32_e32 v118, 0x3fb8aa3b, v118
	v_mul_f32_e32 v119, 0x3fb8aa3b, v119
	v_exp_f32_e32 v4, v4
	v_exp_f32_e32 v5, v5
	v_exp_f32_e32 v118, v118
	v_exp_f32_e32 v119, v119
	v_add_f32_e32 v4, 1.0, v4
	v_add_f32_e32 v5, 1.0, v5
	v_add_f32_e32 v118, 1.0, v118
	v_add_f32_e32 v119, 1.0, v119
	v_rcp_f32_e32 v4, v4
	v_rcp_f32_e32 v118, v118
	v_rcp_f32_e32 v119, v119
	v_rcp_f32_e32 v5, v5
	v_pk_mul_f32 v[112:113], v[112:113], v[118:119]
	v_pk_mul_f32 v[116:117], v[116:117], v[4:5]
; DEVI float gelu_f(float x) {
;   float u = 0.7978845608028654f * (x + 0.044715f * x * x * x);
;   return x * __builtin_amdgcn_rcpf(1.f + __expf(-2.f * u));
; }
; DEVI void phase2(const Params& p, int l, char* lds) {
;     ...
; #pragma unroll
;     for (int ni = 0; ni < 4; ++ni)
; #pragma unroll
;       for (int mi = 0; mi < 8; ++mi) {
;         f32x4 v = acc[ni][mi];
;         if (do_gelu) { v[0] = gelu_f(v[0]); v[1] = gelu_f(v[1]); v[2] = gelu_f(v[2]); v[3] = gelu_f(v[3]); }
;         int n = n0 + wn * 64 + ni * 16 + fq * 4;
;         int m = m0 + wm * 128 + mi * 16 + fr;
;         store_bf4(proj + (long)m * LDP + n, v);
;       }
.LBB0_703:
	v_or_b32_e32 v4, 64, v138
	v_mad_i64_i32 v[118:119], s[28:29], v4, s72, v[2:3]
	v_cvt_pk_bf16_f32 v212, v116, v117
	v_cvt_pk_bf16_f32 v213, v112, v113
	s_and_b64 vcc, exec, s[40:41]
	s_cbranch_vccnz .LBB0_705
	v_mul_f32_e32 v4, 0x3d372713, v110
	v_mul_f32_e32 v5, 0x3d372713, v111
	v_mul_f32_e32 v112, 0x3d372713, v108
	v_mul_f32_e32 v113, 0x3d372713, v109
	v_mul_f32_e32 v4, v110, v4
	v_mul_f32_e32 v5, v111, v5
	v_mul_f32_e32 v112, v108, v112
	v_mul_f32_e32 v113, v109, v113
	v_fma_f32 v4, v110, v4, v110
	v_fma_f32 v5, v111, v5, v111
	v_fma_f32 v112, v108, v112, v108
	v_fma_f32 v113, v109, v113, v109
	v_mul_f32_e32 v4, 0x3f4c422a, v4
	v_mul_f32_e32 v5, 0x3f4c422a, v5
	v_mul_f32_e32 v112, 0x3f4c422a, v112
	v_mul_f32_e32 v113, 0x3f4c422a, v113
	v_mul_f32_e32 v4, -2.0, v4
	v_mul_f32_e32 v5, -2.0, v5
	v_mul_f32_e32 v112, -2.0, v112
	v_mul_f32_e32 v113, -2.0, v113
	v_mul_f32_e32 v4, 0x3fb8aa3b, v4
	v_mul_f32_e32 v5, 0x3fb8aa3b, v5
	v_mul_f32_e32 v112, 0x3fb8aa3b, v112
	v_mul_f32_e32 v113, 0x3fb8aa3b, v113
	v_exp_f32_e32 v4, v4
	v_exp_f32_e32 v5, v5
	v_exp_f32_e32 v112, v112
	v_exp_f32_e32 v113, v113
	v_add_f32_e32 v4, 1.0, v4
	v_add_f32_e32 v5, 1.0, v5
	v_add_f32_e32 v112, 1.0, v112
	v_add_f32_e32 v113, 1.0, v113
	v_rcp_f32_e32 v4, v4
	v_rcp_f32_e32 v112, v112
	v_rcp_f32_e32 v113, v113
	v_rcp_f32_e32 v5, v5
	v_pk_mul_f32 v[108:109], v[108:109], v[112:113]
	v_pk_mul_f32 v[110:111], v[110:111], v[4:5]
.LBB0_705:
	v_or_b32_e32 v4, 0x50, v138
	v_mad_i64_i32 v[112:113], s[28:29], v4, s72, v[2:3]
	v_cvt_pk_bf16_f32 v216, v110, v111
	v_cvt_pk_bf16_f32 v217, v108, v109
	s_and_b64 vcc, exec, s[40:41]
	s_cbranch_vccnz .LBB0_707
	v_mul_f32_e32 v4, 0x3d372713, v106
	v_mul_f32_e32 v5, 0x3d372713, v107
	v_mul_f32_e32 v108, 0x3d372713, v84
	v_mul_f32_e32 v109, 0x3d372713, v85
	v_mul_f32_e32 v4, v106, v4
	v_mul_f32_e32 v5, v107, v5
	v_mul_f32_e32 v108, v84, v108
	v_mul_f32_e32 v109, v85, v109
	v_fma_f32 v4, v106, v4, v106
	v_fma_f32 v5, v107, v5, v107
	v_fma_f32 v108, v84, v108, v84
	v_fma_f32 v109, v85, v109, v85
	v_mul_f32_e32 v4, 0x3f4c422a, v4
	v_mul_f32_e32 v5, 0x3f4c422a, v5
	v_mul_f32_e32 v108, 0x3f4c422a, v108
	v_mul_f32_e32 v109, 0x3f4c422a, v109
	v_mul_f32_e32 v4, -2.0, v4
	v_mul_f32_e32 v5, -2.0, v5
	v_mul_f32_e32 v108, -2.0, v108
	v_mul_f32_e32 v109, -2.0, v109
	v_mul_f32_e32 v4, 0x3fb8aa3b, v4
	v_mul_f32_e32 v5, 0x3fb8aa3b, v5
	v_mul_f32_e32 v108, 0x3fb8aa3b, v108
	v_mul_f32_e32 v109, 0x3fb8aa3b, v109
	v_exp_f32_e32 v4, v4
	v_exp_f32_e32 v5, v5
	v_exp_f32_e32 v108, v108
	v_exp_f32_e32 v109, v109
	v_add_f32_e32 v4, 1.0, v4
	v_add_f32_e32 v5, 1.0, v5
	v_add_f32_e32 v108, 1.0, v108
	v_add_f32_e32 v109, 1.0, v109
	v_rcp_f32_e32 v4, v4
	v_rcp_f32_e32 v108, v108
	v_rcp_f32_e32 v109, v109
	v_rcp_f32_e32 v5, v5
	v_pk_mul_f32 v[84:85], v[84:85], v[108:109]
	v_pk_mul_f32 v[106:107], v[106:107], v[4:5]
.LBB0_707:
	v_or_b32_e32 v4, 0x60, v138
	v_mad_i64_i32 v[4:5], s[28:29], v4, s72, v[2:3]
	v_cvt_pk_bf16_f32 v234, v106, v107
	v_cvt_pk_bf16_f32 v235, v84, v85
	s_and_b64 vcc, exec, s[40:41]
	s_cbranch_vccnz .LBB0_709
	v_mul_f32_e32 v84, 0x3d372713, v58
	v_mul_f32_e32 v85, 0x3d372713, v59
	v_mul_f32_e32 v106, 0x3d372713, v60
	v_mul_f32_e32 v107, 0x3d372713, v61
	v_mul_f32_e32 v84, v58, v84
	v_mul_f32_e32 v85, v59, v85
	v_mul_f32_e32 v106, v60, v106
	v_mul_f32_e32 v107, v61, v107
	v_fma_f32 v84, v58, v84, v58
	v_fma_f32 v85, v59, v85, v59
	v_fma_f32 v106, v60, v106, v60
	v_fma_f32 v107, v61, v107, v61
	v_mul_f32_e32 v84, 0x3f4c422a, v84
	v_mul_f32_e32 v85, 0x3f4c422a, v85
	v_mul_f32_e32 v106, 0x3f4c422a, v106
	v_mul_f32_e32 v107, 0x3f4c422a, v107
	v_mul_f32_e32 v84, -2.0, v84
	v_mul_f32_e32 v85, -2.0, v85
	v_mul_f32_e32 v106, -2.0, v106
	v_mul_f32_e32 v107, -2.0, v107
	v_mul_f32_e32 v84, 0x3fb8aa3b, v84
	v_mul_f32_e32 v85, 0x3fb8aa3b, v85
	v_mul_f32_e32 v106, 0x3fb8aa3b, v106
	v_mul_f32_e32 v107, 0x3fb8aa3b, v107
	v_exp_f32_e32 v84, v84
	v_exp_f32_e32 v85, v85
	v_exp_f32_e32 v106, v106
	v_exp_f32_e32 v107, v107
	v_add_f32_e32 v84, 1.0, v84
	v_add_f32_e32 v85, 1.0, v85
	v_add_f32_e32 v106, 1.0, v106
	v_add_f32_e32 v107, 1.0, v107
	v_rcp_f32_e32 v84, v84
	v_rcp_f32_e32 v106, v106
	v_rcp_f32_e32 v107, v107
	v_rcp_f32_e32 v85, v85
	v_pk_mul_f32 v[60:61], v[60:61], v[106:107]
	v_pk_mul_f32 v[58:59], v[58:59], v[84:85]
.LBB0_709:
	v_or_b32_e32 v84, 0x70, v138
	v_mad_i64_i32 v[2:3], s[28:29], v84, s72, v[2:3]
	v_cvt_pk_bf16_f32 v238, v58, v59
	v_cvt_pk_bf16_f32 v239, v60, v61
	s_mov_b64 s[36:37], -1
	s_and_b64 vcc, exec, s[0:1]
	s_cbranch_vccz .LBB0_711
	v_cvt_pk_bf16_f32 v198, v114, v115
	v_cvt_pk_bf16_f32 v199, v104, v105
	v_lshl_add_u64 v[132:133], v[132:133], 0, v[254:255]
	s_nop 1
	v_permlane16_swap_b32_e32 v196, v198
	v_permlane16_swap_b32_e32 v197, v199
	s_nop 1
	global_store_dwordx4 v[132:133], v[196:199], off
	s_mov_b64 s[36:37], 0
; DEVI float gelu_f(float x) {
;   float u = 0.7978845608028654f * (x + 0.044715f * x * x * x);
;   return x * __builtin_amdgcn_rcpf(1.f + __expf(-2.f * u));
; }
; DEVI void phase2(const Params& p, int l, char* lds) {
;     ...
; #pragma unroll
;     for (int ni = 0; ni < 4; ++ni)
; #pragma unroll
;       for (int mi = 0; mi < 8; ++mi) {
;         f32x4 v = acc[ni][mi];
;         if (do_gelu) { v[0] = gelu_f(v[0]); v[1] = gelu_f(v[1]); v[2] = gelu_f(v[2]); v[3] = gelu_f(v[3]); }
;         int n = n0 + wn * 64 + ni * 16 + fq * 4;
;         int m = m0 + wm * 128 + mi * 16 + fr;
;         store_bf4(proj + (long)m * LDP + n, v);
;       }
.LBB0_711:
	s_andn2_b64 vcc, exec, s[36:37]
	s_cbranch_vccnz .LBB0_713
	v_mul_f32_e32 v58, 0x3d372713, v114
	v_mul_f32_e32 v59, 0x3d372713, v115
	v_mul_f32_e32 v60, 0x3d372713, v104
	v_mul_f32_e32 v61, 0x3d372713, v105
	v_mul_f32_e32 v58, v114, v58
	v_mul_f32_e32 v59, v115, v59
	v_mul_f32_e32 v60, v104, v60
	v_mul_f32_e32 v61, v105, v61
	v_fma_f32 v58, v114, v58, v114
	v_fma_f32 v59, v115, v59, v115
	v_fma_f32 v60, v104, v60, v104
	v_fma_f32 v61, v105, v61, v105
	v_mul_f32_e32 v58, 0x3f4c422a, v58
	v_mul_f32_e32 v59, 0x3f4c422a, v59
	v_mul_f32_e32 v60, 0x3f4c422a, v60
	v_mul_f32_e32 v61, 0x3f4c422a, v61
	v_mul_f32_e32 v58, -2.0, v58
	v_mul_f32_e32 v59, -2.0, v59
	v_mul_f32_e32 v60, -2.0, v60
	v_mul_f32_e32 v61, -2.0, v61
	v_mul_f32_e32 v58, 0x3fb8aa3b, v58
	v_mul_f32_e32 v59, 0x3fb8aa3b, v59
	v_mul_f32_e32 v60, 0x3fb8aa3b, v60
	v_mul_f32_e32 v61, 0x3fb8aa3b, v61
	v_exp_f32_e32 v58, v58
	v_exp_f32_e32 v59, v59
	v_exp_f32_e32 v60, v60
	v_exp_f32_e32 v61, v61
	v_add_f32_e32 v58, 1.0, v58
	v_add_f32_e32 v59, 1.0, v59
	v_add_f32_e32 v60, 1.0, v60
	v_add_f32_e32 v61, 1.0, v61
	v_rcp_f32_e32 v58, v58
	v_rcp_f32_e32 v59, v59
	v_rcp_f32_e32 v60, v60
	v_rcp_f32_e32 v61, v61
	v_pk_mul_f32 v[58:59], v[114:115], v[58:59]
	s_nop 0
	v_cvt_pk_bf16_f32 v198, v58, v59
	v_pk_mul_f32 v[60:61], v[104:105], v[60:61]
	s_nop 0
	v_cvt_pk_bf16_f32 v199, v60, v61
	v_lshl_add_u64 v[132:133], v[132:133], 0, v[254:255]
	s_nop 1
	v_permlane16_swap_b32_e32 v196, v198
	v_permlane16_swap_b32_e32 v197, v199
	s_nop 1
	global_store_dwordx4 v[132:133], v[196:199], off
	v_mul_f32_e32 v58, 0x3d372713, v98
	v_mul_f32_e32 v59, 0x3d372713, v99
	v_mul_f32_e32 v60, 0x3d372713, v100
	v_mul_f32_e32 v61, 0x3d372713, v101
	v_mul_f32_e32 v58, v98, v58
	v_mul_f32_e32 v59, v99, v59
	v_mul_f32_e32 v60, v100, v60
	v_mul_f32_e32 v61, v101, v61
	v_fma_f32 v58, v98, v58, v98
	v_fma_f32 v59, v99, v59, v99
	v_fma_f32 v60, v100, v60, v100
	v_fma_f32 v61, v101, v61, v101
	v_mul_f32_e32 v58, 0x3f4c422a, v58
	v_mul_f32_e32 v59, 0x3f4c422a, v59
	v_mul_f32_e32 v60, 0x3f4c422a, v60
	v_mul_f32_e32 v61, 0x3f4c422a, v61
	v_mul_f32_e32 v58, -2.0, v58
	v_mul_f32_e32 v59, -2.0, v59
	v_mul_f32_e32 v60, -2.0, v60
	v_mul_f32_e32 v61, -2.0, v61
	v_mul_f32_e32 v58, 0x3fb8aa3b, v58
	v_mul_f32_e32 v59, 0x3fb8aa3b, v59
	v_mul_f32_e32 v60, 0x3fb8aa3b, v60
	v_mul_f32_e32 v61, 0x3fb8aa3b, v61
	v_exp_f32_e32 v58, v58
	v_exp_f32_e32 v59, v59
	v_exp_f32_e32 v60, v60
	v_exp_f32_e32 v61, v61
	v_add_f32_e32 v58, 1.0, v58
	v_add_f32_e32 v59, 1.0, v59
	v_add_f32_e32 v60, 1.0, v60
	v_add_f32_e32 v61, 1.0, v61
	v_rcp_f32_e32 v58, v58
	v_rcp_f32_e32 v59, v59
	v_rcp_f32_e32 v60, v60
	v_rcp_f32_e32 v61, v61
	v_pk_mul_f32 v[98:99], v[98:99], v[58:59]
	v_pk_mul_f32 v[100:101], v[100:101], v[60:61]
.LBB0_713:
	v_cvt_pk_bf16_f32 v202, v98, v99
	v_cvt_pk_bf16_f32 v203, v100, v101
	s_mov_b64 s[36:37], -1
	s_and_b64 vcc, exec, s[0:1]
	v_lshl_add_u64 v[130:131], v[130:131], 0, v[254:255]
	s_nop 1
	v_permlane16_swap_b32_e32 v200, v202
	v_permlane16_swap_b32_e32 v201, v203
	s_nop 1
	global_store_dwordx4 v[130:131], v[200:203], off
	s_cbranch_vccz .LBB0_715
	v_cvt_pk_bf16_f32 v206, v102, v103
	v_cvt_pk_bf16_f32 v207, v96, v97
	v_lshl_add_u64 v[126:127], v[126:127], 0, v[254:255]
	s_nop 1
	v_permlane16_swap_b32_e32 v204, v206
	v_permlane16_swap_b32_e32 v205, v207
	s_nop 1
	global_store_dwordx4 v[126:127], v[204:207], off
	s_mov_b64 s[36:37], 0
.LBB0_715:
	s_andn2_b64 vcc, exec, s[36:37]
	s_cbranch_vccnz .LBB0_717
	v_mul_f32_e32 v58, 0x3d372713, v102
	v_mul_f32_e32 v59, 0x3d372713, v103
	v_mul_f32_e32 v60, 0x3d372713, v96
	v_mul_f32_e32 v61, 0x3d372713, v97
	v_mul_f32_e32 v58, v102, v58
	v_mul_f32_e32 v59, v103, v59
	v_mul_f32_e32 v60, v96, v60
	v_mul_f32_e32 v61, v97, v61
	v_fma_f32 v58, v102, v58, v102
	v_fma_f32 v59, v103, v59, v103
	v_fma_f32 v60, v96, v60, v96
	v_fma_f32 v61, v97, v61, v97
	v_mul_f32_e32 v58, 0x3f4c422a, v58
	v_mul_f32_e32 v59, 0x3f4c422a, v59
	v_mul_f32_e32 v60, 0x3f4c422a, v60
	v_mul_f32_e32 v61, 0x3f4c422a, v61
	v_mul_f32_e32 v58, -2.0, v58
	v_mul_f32_e32 v59, -2.0, v59
	v_mul_f32_e32 v60, -2.0, v60
	v_mul_f32_e32 v61, -2.0, v61
	v_mul_f32_e32 v58, 0x3fb8aa3b, v58
	v_mul_f32_e32 v59, 0x3fb8aa3b, v59
	v_mul_f32_e32 v60, 0x3fb8aa3b, v60
	v_mul_f32_e32 v61, 0x3fb8aa3b, v61
	v_exp_f32_e32 v58, v58
	v_exp_f32_e32 v59, v59
	v_exp_f32_e32 v60, v60
	v_exp_f32_e32 v61, v61
	v_add_f32_e32 v58, 1.0, v58
	v_add_f32_e32 v59, 1.0, v59
	v_add_f32_e32 v60, 1.0, v60
	v_add_f32_e32 v61, 1.0, v61
	v_rcp_f32_e32 v58, v58
	v_rcp_f32_e32 v59, v59
	v_rcp_f32_e32 v60, v60
	v_rcp_f32_e32 v61, v61
	v_pk_mul_f32 v[58:59], v[102:103], v[58:59]
	s_nop 0
	v_cvt_pk_bf16_f32 v206, v58, v59
	v_pk_mul_f32 v[60:61], v[96:97], v[60:61]
	s_nop 0
	v_cvt_pk_bf16_f32 v207, v60, v61
	v_lshl_add_u64 v[126:127], v[126:127], 0, v[254:255]
	s_nop 1
	v_permlane16_swap_b32_e32 v204, v206
	v_permlane16_swap_b32_e32 v205, v207
	s_nop 1
	global_store_dwordx4 v[126:127], v[204:207], off
	v_mul_f32_e32 v58, 0x3d372713, v90
	v_mul_f32_e32 v59, 0x3d372713, v91
	v_mul_f32_e32 v60, 0x3d372713, v92
	v_mul_f32_e32 v61, 0x3d372713, v93
	v_mul_f32_e32 v58, v90, v58
	v_mul_f32_e32 v59, v91, v59
	v_mul_f32_e32 v60, v92, v60
	v_mul_f32_e32 v61, v93, v61
	v_fma_f32 v58, v90, v58, v90
	v_fma_f32 v59, v91, v59, v91
	v_fma_f32 v60, v92, v60, v92
	v_fma_f32 v61, v93, v61, v93
	v_mul_f32_e32 v58, 0x3f4c422a, v58
	v_mul_f32_e32 v59, 0x3f4c422a, v59
	v_mul_f32_e32 v60, 0x3f4c422a, v60
	v_mul_f32_e32 v61, 0x3f4c422a, v61
	v_mul_f32_e32 v58, -2.0, v58
	v_mul_f32_e32 v59, -2.0, v59
	v_mul_f32_e32 v60, -2.0, v60
	v_mul_f32_e32 v61, -2.0, v61
	v_mul_f32_e32 v58, 0x3fb8aa3b, v58
	v_mul_f32_e32 v59, 0x3fb8aa3b, v59
	v_mul_f32_e32 v60, 0x3fb8aa3b, v60
	v_mul_f32_e32 v61, 0x3fb8aa3b, v61
	v_exp_f32_e32 v58, v58
	v_exp_f32_e32 v59, v59
	v_exp_f32_e32 v60, v60
	v_exp_f32_e32 v61, v61
	v_add_f32_e32 v58, 1.0, v58
	v_add_f32_e32 v59, 1.0, v59
	v_add_f32_e32 v60, 1.0, v60
	v_add_f32_e32 v61, 1.0, v61
	v_rcp_f32_e32 v58, v58
	v_rcp_f32_e32 v59, v59
	v_rcp_f32_e32 v60, v60
	v_rcp_f32_e32 v61, v61
	v_pk_mul_f32 v[90:91], v[90:91], v[58:59]
	v_pk_mul_f32 v[92:93], v[92:93], v[60:61]
; DEVI float gelu_f(float x) {
;   float u = 0.7978845608028654f * (x + 0.044715f * x * x * x);
;   return x * __builtin_amdgcn_rcpf(1.f + __expf(-2.f * u));
; }
; DEVI void phase2(const Params& p, int l, char* lds) {
;     ...
; #pragma unroll
;     for (int ni = 0; ni < 4; ++ni)
; #pragma unroll
;       for (int mi = 0; mi < 8; ++mi) {
;         f32x4 v = acc[ni][mi];
;         if (do_gelu) { v[0] = gelu_f(v[0]); v[1] = gelu_f(v[1]); v[2] = gelu_f(v[2]); v[3] = gelu_f(v[3]); }
;         int n = n0 + wn * 64 + ni * 16 + fq * 4;
;         int m = m0 + wm * 128 + mi * 16 + fr;
;         store_bf4(proj + (long)m * LDP + n, v);
;       }
.LBB0_717:
	v_cvt_pk_bf16_f32 v210, v90, v91
	v_cvt_pk_bf16_f32 v211, v92, v93
	s_mov_b64 s[36:37], -1
	s_and_b64 vcc, exec, s[0:1]
	v_lshl_add_u64 v[122:123], v[122:123], 0, v[254:255]
	s_nop 1
	v_permlane16_swap_b32_e32 v208, v210
	v_permlane16_swap_b32_e32 v209, v211
	s_nop 1
	global_store_dwordx4 v[122:123], v[208:211], off
	s_cbranch_vccz .LBB0_719
	v_cvt_pk_bf16_f32 v214, v94, v95
	v_cvt_pk_bf16_f32 v215, v88, v89
	v_lshl_add_u64 v[118:119], v[118:119], 0, v[254:255]
	s_nop 1
	v_permlane16_swap_b32_e32 v212, v214
	v_permlane16_swap_b32_e32 v213, v215
	s_nop 1
	global_store_dwordx4 v[118:119], v[212:215], off
	s_mov_b64 s[36:37], 0
.LBB0_719:
	s_andn2_b64 vcc, exec, s[36:37]
	s_cbranch_vccnz .LBB0_721
	v_mul_f32_e32 v58, 0x3d372713, v94
	v_mul_f32_e32 v59, 0x3d372713, v95
	v_mul_f32_e32 v60, 0x3d372713, v88
	v_mul_f32_e32 v61, 0x3d372713, v89
	v_mul_f32_e32 v58, v94, v58
	v_mul_f32_e32 v59, v95, v59
	v_mul_f32_e32 v60, v88, v60
	v_mul_f32_e32 v61, v89, v61
	v_fma_f32 v58, v94, v58, v94
	v_fma_f32 v59, v95, v59, v95
	v_fma_f32 v60, v88, v60, v88
	v_fma_f32 v61, v89, v61, v89
	v_mul_f32_e32 v58, 0x3f4c422a, v58
	v_mul_f32_e32 v59, 0x3f4c422a, v59
	v_mul_f32_e32 v60, 0x3f4c422a, v60
	v_mul_f32_e32 v61, 0x3f4c422a, v61
	v_mul_f32_e32 v58, -2.0, v58
	v_mul_f32_e32 v59, -2.0, v59
	v_mul_f32_e32 v60, -2.0, v60
	v_mul_f32_e32 v61, -2.0, v61
	v_mul_f32_e32 v58, 0x3fb8aa3b, v58
	v_mul_f32_e32 v59, 0x3fb8aa3b, v59
	v_mul_f32_e32 v60, 0x3fb8aa3b, v60
	v_mul_f32_e32 v61, 0x3fb8aa3b, v61
	v_exp_f32_e32 v58, v58
	v_exp_f32_e32 v59, v59
	v_exp_f32_e32 v60, v60
	v_exp_f32_e32 v61, v61
	v_add_f32_e32 v58, 1.0, v58
	v_add_f32_e32 v59, 1.0, v59
	v_add_f32_e32 v60, 1.0, v60
	v_add_f32_e32 v61, 1.0, v61
	v_rcp_f32_e32 v58, v58
	v_rcp_f32_e32 v59, v59
	v_rcp_f32_e32 v60, v60
	v_rcp_f32_e32 v61, v61
	v_pk_mul_f32 v[58:59], v[94:95], v[58:59]
	s_nop 0
	v_cvt_pk_bf16_f32 v214, v58, v59
	v_pk_mul_f32 v[60:61], v[88:89], v[60:61]
	s_nop 0
	v_cvt_pk_bf16_f32 v215, v60, v61
	v_lshl_add_u64 v[118:119], v[118:119], 0, v[254:255]
	s_nop 1
	v_permlane16_swap_b32_e32 v212, v214
	v_permlane16_swap_b32_e32 v213, v215
	s_nop 1
	global_store_dwordx4 v[118:119], v[212:215], off
	v_mul_f32_e32 v58, 0x3d372713, v86
	v_mul_f32_e32 v59, 0x3d372713, v87
	v_mul_f32_e32 v60, 0x3d372713, v80
	v_mul_f32_e32 v61, 0x3d372713, v81
	v_mul_f32_e32 v58, v86, v58
	v_mul_f32_e32 v59, v87, v59
	v_mul_f32_e32 v60, v80, v60
	v_mul_f32_e32 v61, v81, v61
	v_fma_f32 v58, v86, v58, v86
	v_fma_f32 v59, v87, v59, v87
	v_fma_f32 v60, v80, v60, v80
	v_fma_f32 v61, v81, v61, v81
	v_mul_f32_e32 v58, 0x3f4c422a, v58
	v_mul_f32_e32 v59, 0x3f4c422a, v59
	v_mul_f32_e32 v60, 0x3f4c422a, v60
	v_mul_f32_e32 v61, 0x3f4c422a, v61
	v_mul_f32_e32 v58, -2.0, v58
	v_mul_f32_e32 v59, -2.0, v59
	v_mul_f32_e32 v60, -2.0, v60
	v_mul_f32_e32 v61, -2.0, v61
	v_mul_f32_e32 v58, 0x3fb8aa3b, v58
	v_mul_f32_e32 v59, 0x3fb8aa3b, v59
	v_mul_f32_e32 v60, 0x3fb8aa3b, v60
	v_mul_f32_e32 v61, 0x3fb8aa3b, v61
	v_exp_f32_e32 v58, v58
	v_exp_f32_e32 v59, v59
	v_exp_f32_e32 v60, v60
	v_exp_f32_e32 v61, v61
	v_add_f32_e32 v58, 1.0, v58
	v_add_f32_e32 v59, 1.0, v59
	v_add_f32_e32 v60, 1.0, v60
	v_add_f32_e32 v61, 1.0, v61
	v_rcp_f32_e32 v58, v58
	v_rcp_f32_e32 v59, v59
	v_rcp_f32_e32 v60, v60
	v_rcp_f32_e32 v61, v61
	v_pk_mul_f32 v[86:87], v[86:87], v[58:59]
	v_pk_mul_f32 v[80:81], v[80:81], v[60:61]
.LBB0_721:
	v_cvt_pk_bf16_f32 v218, v86, v87
	v_cvt_pk_bf16_f32 v219, v80, v81
	s_mov_b64 s[36:37], -1
	s_and_b64 vcc, exec, s[0:1]
	v_lshl_add_u64 v[112:113], v[112:113], 0, v[254:255]
	s_nop 1
	v_permlane16_swap_b32_e32 v216, v218
	v_permlane16_swap_b32_e32 v217, v219
	s_nop 1
	global_store_dwordx4 v[112:113], v[216:219], off
	s_cbranch_vccz .LBB0_723
	v_cvt_pk_bf16_f32 v236, v82, v83
	v_cvt_pk_bf16_f32 v237, v78, v79
	v_lshl_add_u64 v[4:5], v[4:5], 0, v[254:255]
	s_nop 1
	v_permlane16_swap_b32_e32 v234, v236
	v_permlane16_swap_b32_e32 v235, v237
	s_nop 1
	global_store_dwordx4 v[4:5], v[234:237], off
	s_mov_b64 s[36:37], 0
.LBB0_723:
	s_andn2_b64 vcc, exec, s[36:37]
	s_cbranch_vccnz .LBB0_725
	v_mul_f32_e32 v58, 0x3d372713, v82
	v_mul_f32_e32 v59, 0x3d372713, v83
	v_mul_f32_e32 v60, 0x3d372713, v78
	v_mul_f32_e32 v61, 0x3d372713, v79
	v_mul_f32_e32 v58, v82, v58
	v_mul_f32_e32 v59, v83, v59
	v_mul_f32_e32 v60, v78, v60
	v_mul_f32_e32 v61, v79, v61
	v_fma_f32 v58, v82, v58, v82
	v_fma_f32 v59, v83, v59, v83
	v_fma_f32 v60, v78, v60, v78
	v_fma_f32 v61, v79, v61, v79
	v_mul_f32_e32 v58, 0x3f4c422a, v58
	v_mul_f32_e32 v59, 0x3f4c422a, v59
	v_mul_f32_e32 v60, 0x3f4c422a, v60
	v_mul_f32_e32 v61, 0x3f4c422a, v61
	v_mul_f32_e32 v58, -2.0, v58
	v_mul_f32_e32 v59, -2.0, v59
	v_mul_f32_e32 v60, -2.0, v60
	v_mul_f32_e32 v61, -2.0, v61
	v_mul_f32_e32 v58, 0x3fb8aa3b, v58
	v_mul_f32_e32 v59, 0x3fb8aa3b, v59
	v_mul_f32_e32 v60, 0x3fb8aa3b, v60
	v_mul_f32_e32 v61, 0x3fb8aa3b, v61
	v_exp_f32_e32 v58, v58
	v_exp_f32_e32 v59, v59
	v_exp_f32_e32 v60, v60
	v_exp_f32_e32 v61, v61
	v_add_f32_e32 v58, 1.0, v58
	v_add_f32_e32 v59, 1.0, v59
	v_add_f32_e32 v60, 1.0, v60
	v_add_f32_e32 v61, 1.0, v61
	v_rcp_f32_e32 v58, v58
	v_rcp_f32_e32 v59, v59
	v_rcp_f32_e32 v60, v60
	v_rcp_f32_e32 v61, v61
	v_pk_mul_f32 v[58:59], v[82:83], v[58:59]
	s_nop 0
	v_cvt_pk_bf16_f32 v236, v58, v59
	v_pk_mul_f32 v[60:61], v[78:79], v[60:61]
	s_nop 0
	v_cvt_pk_bf16_f32 v237, v60, v61
	v_lshl_add_u64 v[4:5], v[4:5], 0, v[254:255]
	s_nop 1
	v_permlane16_swap_b32_e32 v234, v236
	v_permlane16_swap_b32_e32 v235, v237
	s_nop 1
	global_store_dwordx4 v[4:5], v[234:237], off
	v_mul_f32_e32 v58, 0x3d372713, v48
	v_mul_f32_e32 v59, 0x3d372713, v49
	v_mul_f32_e32 v60, 0x3d372713, v46
	v_mul_f32_e32 v61, 0x3d372713, v47
	v_mul_f32_e32 v58, v48, v58
	v_mul_f32_e32 v59, v49, v59
	v_mul_f32_e32 v60, v46, v60
	v_mul_f32_e32 v61, v47, v61
	v_fma_f32 v58, v48, v58, v48
	v_fma_f32 v59, v49, v59, v49
	v_fma_f32 v60, v46, v60, v46
	v_fma_f32 v61, v47, v61, v47
	v_mul_f32_e32 v58, 0x3f4c422a, v58
	v_mul_f32_e32 v59, 0x3f4c422a, v59
	v_mul_f32_e32 v60, 0x3f4c422a, v60
	v_mul_f32_e32 v61, 0x3f4c422a, v61
	v_mul_f32_e32 v58, -2.0, v58
	v_mul_f32_e32 v59, -2.0, v59
	v_mul_f32_e32 v60, -2.0, v60
	v_mul_f32_e32 v61, -2.0, v61
	v_mul_f32_e32 v58, 0x3fb8aa3b, v58
	v_mul_f32_e32 v59, 0x3fb8aa3b, v59
	v_mul_f32_e32 v60, 0x3fb8aa3b, v60
	v_mul_f32_e32 v61, 0x3fb8aa3b, v61
	v_exp_f32_e32 v58, v58
	v_exp_f32_e32 v59, v59
	v_exp_f32_e32 v60, v60
	v_exp_f32_e32 v61, v61
	v_add_f32_e32 v58, 1.0, v58
	v_add_f32_e32 v59, 1.0, v59
	v_add_f32_e32 v60, 1.0, v60
	v_add_f32_e32 v61, 1.0, v61
	v_rcp_f32_e32 v58, v58
	v_rcp_f32_e32 v59, v59
	v_rcp_f32_e32 v60, v60
	v_rcp_f32_e32 v61, v61
	v_pk_mul_f32 v[48:49], v[48:49], v[58:59]
	v_pk_mul_f32 v[46:47], v[46:47], v[60:61]
; DEVI float gelu_f(float x) {
;   float u = 0.7978845608028654f * (x + 0.044715f * x * x * x);
;   return x * __builtin_amdgcn_rcpf(1.f + __expf(-2.f * u));
; }
; DEVI void phase2(const Params& p, int l, char* lds) {
;     ...
; #pragma unroll
;     for (int ni = 0; ni < 4; ++ni)
; #pragma unroll
;       for (int mi = 0; mi < 8; ++mi) {
;         f32x4 v = acc[ni][mi];
;         if (do_gelu) { v[0] = gelu_f(v[0]); v[1] = gelu_f(v[1]); v[2] = gelu_f(v[2]); v[3] = gelu_f(v[3]); }
;         int n = n0 + wn * 64 + ni * 16 + fq * 4;
;         int m = m0 + wm * 128 + mi * 16 + fr;
;         store_bf4(proj + (long)m * LDP + n, v);
;       }
.LBB0_725:
	v_cvt_pk_bf16_f32 v240, v48, v49
	v_cvt_pk_bf16_f32 v241, v46, v47
	s_mov_b64 s[36:37], -1
	s_and_b64 vcc, exec, s[0:1]
	v_lshl_add_u64 v[2:3], v[2:3], 0, v[254:255]
	s_nop 1
	v_permlane16_swap_b32_e32 v238, v240
	v_permlane16_swap_b32_e32 v239, v241
	s_nop 1
	global_store_dwordx4 v[2:3], v[238:241], off
	s_cbranch_vccz .LBB0_727
	v_cvt_pk_bf16_f32 v196, v74, v75
	v_cvt_pk_bf16_f32 v197, v76, v77
	s_mov_b64 s[36:37], 0
.LBB0_727:
	s_andn2_b64 vcc, exec, s[36:37]
	s_cbranch_vccnz .LBB0_729
	v_mul_f32_e32 v46, 0x3d372713, v74
	v_mul_f32_e32 v46, v74, v46
	v_mov_b32_e32 v47, v74
	v_fmac_f32_e32 v47, v47, v46
	v_mul_f32_e32 v46, 0x3f4c422a, v47
	v_mul_f32_e32 v47, 0x3d372713, v75
	v_mul_f32_e32 v47, v75, v47
	v_mov_b32_e32 v48, v75
	v_fmac_f32_e32 v48, v48, v47
	v_mul_f32_e32 v47, 0x3f4c422a, v48
	v_mul_f32_e32 v48, 0x3d372713, v76
	v_mul_f32_e32 v49, 0x3d372713, v77
	v_mul_f32_e32 v48, v76, v48
	v_mul_f32_e32 v49, v77, v49
	v_fma_f32 v48, v76, v48, v76
	v_fma_f32 v49, v77, v49, v77
	v_mul_f32_e32 v48, 0x3f4c422a, v48
	v_mul_f32_e32 v49, 0x3f4c422a, v49
	v_mul_f32_e32 v46, -2.0, v46
	v_mul_f32_e32 v47, -2.0, v47
	v_mul_f32_e32 v48, -2.0, v48
	v_mul_f32_e32 v49, -2.0, v49
	v_mul_f32_e32 v46, 0x3fb8aa3b, v46
	v_mul_f32_e32 v47, 0x3fb8aa3b, v47
	v_mul_f32_e32 v48, 0x3fb8aa3b, v48
	v_mul_f32_e32 v49, 0x3fb8aa3b, v49
	v_exp_f32_e32 v46, v46
	v_exp_f32_e32 v47, v47
	v_exp_f32_e32 v48, v48
	v_exp_f32_e32 v49, v49
	v_add_f32_e32 v46, 1.0, v46
	v_add_f32_e32 v47, 1.0, v47
	v_add_f32_e32 v48, 1.0, v48
	v_add_f32_e32 v49, 1.0, v49
	v_rcp_f32_e32 v46, v46
	v_rcp_f32_e32 v47, v47
	v_rcp_f32_e32 v48, v48
	v_rcp_f32_e32 v49, v49
	v_pk_mul_f32 v[46:47], v[74:75], v[46:47]
	s_nop 0
	v_cvt_pk_bf16_f32 v196, v46, v47
	v_pk_mul_f32 v[48:49], v[76:77], v[48:49]
	s_nop 0
	v_cvt_pk_bf16_f32 v197, v48, v49
	v_mul_f32_e32 v46, 0x3d372713, v70
	v_mul_f32_e32 v47, 0x3d372713, v71
	v_mul_f32_e32 v48, 0x3d372713, v72
	v_mul_f32_e32 v49, 0x3d372713, v73
	v_mul_f32_e32 v46, v70, v46
	v_mul_f32_e32 v47, v71, v47
	v_mul_f32_e32 v48, v72, v48
	v_mul_f32_e32 v49, v73, v49
	v_fma_f32 v46, v70, v46, v70
	v_fma_f32 v47, v71, v47, v71
	v_fma_f32 v48, v72, v48, v72
	v_fma_f32 v49, v73, v49, v73
	v_mul_f32_e32 v46, 0x3f4c422a, v46
	v_mul_f32_e32 v47, 0x3f4c422a, v47
	v_mul_f32_e32 v48, 0x3f4c422a, v48
	v_mul_f32_e32 v49, 0x3f4c422a, v49
	v_mul_f32_e32 v46, -2.0, v46
	v_mul_f32_e32 v47, -2.0, v47
	v_mul_f32_e32 v48, -2.0, v48
	v_mul_f32_e32 v49, -2.0, v49
	v_mul_f32_e32 v46, 0x3fb8aa3b, v46
	v_mul_f32_e32 v47, 0x3fb8aa3b, v47
	v_mul_f32_e32 v48, 0x3fb8aa3b, v48
	v_mul_f32_e32 v49, 0x3fb8aa3b, v49
	v_exp_f32_e32 v46, v46
	v_exp_f32_e32 v47, v47
	v_exp_f32_e32 v48, v48
	v_exp_f32_e32 v49, v49
	v_add_f32_e32 v46, 1.0, v46
	v_add_f32_e32 v47, 1.0, v47
	v_add_f32_e32 v48, 1.0, v48
	v_add_f32_e32 v49, 1.0, v49
	v_rcp_f32_e32 v46, v46
	v_rcp_f32_e32 v47, v47
	v_rcp_f32_e32 v48, v48
	v_rcp_f32_e32 v49, v49
	v_pk_mul_f32 v[70:71], v[70:71], v[46:47]
	v_pk_mul_f32 v[72:73], v[72:73], v[48:49]
.LBB0_729:
	v_cvt_pk_bf16_f32 v200, v70, v71
	v_cvt_pk_bf16_f32 v201, v72, v73
	s_mov_b64 s[36:37], -1
	s_and_b64 vcc, exec, s[0:1]
	s_cbranch_vccz .LBB0_731
	v_cvt_pk_bf16_f32 v204, v66, v67
	v_cvt_pk_bf16_f32 v205, v68, v69
	s_mov_b64 s[36:37], 0
.LBB0_731:
	s_andn2_b64 vcc, exec, s[36:37]
	s_cbranch_vccnz .LBB0_733
	v_mul_f32_e32 v46, 0x3d372713, v66
	v_mul_f32_e32 v47, 0x3d372713, v67
	v_mul_f32_e32 v48, 0x3d372713, v68
	v_mul_f32_e32 v49, 0x3d372713, v69
	v_mul_f32_e32 v46, v66, v46
	v_mul_f32_e32 v47, v67, v47
	v_mul_f32_e32 v48, v68, v48
	v_mul_f32_e32 v49, v69, v49
	v_fma_f32 v46, v66, v46, v66
	v_fma_f32 v47, v67, v47, v67
	v_fma_f32 v48, v68, v48, v68
	v_fma_f32 v49, v69, v49, v69
	v_mul_f32_e32 v46, 0x3f4c422a, v46
	v_mul_f32_e32 v47, 0x3f4c422a, v47
	v_mul_f32_e32 v48, 0x3f4c422a, v48
	v_mul_f32_e32 v49, 0x3f4c422a, v49
	v_mul_f32_e32 v46, -2.0, v46
	v_mul_f32_e32 v47, -2.0, v47
	v_mul_f32_e32 v48, -2.0, v48
	v_mul_f32_e32 v49, -2.0, v49
	v_mul_f32_e32 v46, 0x3fb8aa3b, v46
	v_mul_f32_e32 v47, 0x3fb8aa3b, v47
	v_mul_f32_e32 v48, 0x3fb8aa3b, v48
	v_mul_f32_e32 v49, 0x3fb8aa3b, v49
	v_exp_f32_e32 v46, v46
	v_exp_f32_e32 v47, v47
	v_exp_f32_e32 v48, v48
	v_exp_f32_e32 v49, v49
	v_add_f32_e32 v46, 1.0, v46
	v_add_f32_e32 v47, 1.0, v47
	v_add_f32_e32 v48, 1.0, v48
	v_add_f32_e32 v49, 1.0, v49
	v_rcp_f32_e32 v46, v46
	v_rcp_f32_e32 v47, v47
	v_rcp_f32_e32 v48, v48
	v_rcp_f32_e32 v49, v49
	v_pk_mul_f32 v[46:47], v[66:67], v[46:47]
	s_nop 0
	v_cvt_pk_bf16_f32 v204, v46, v47
	v_pk_mul_f32 v[48:49], v[68:69], v[48:49]
	s_nop 0
	v_cvt_pk_bf16_f32 v205, v48, v49
	v_mul_f32_e32 v46, 0x3d372713, v62
	v_mul_f32_e32 v47, 0x3d372713, v63
	v_mul_f32_e32 v48, 0x3d372713, v64
	v_mul_f32_e32 v49, 0x3d372713, v65
	v_mul_f32_e32 v46, v62, v46
	v_mul_f32_e32 v47, v63, v47
	v_mul_f32_e32 v48, v64, v48
	v_mul_f32_e32 v49, v65, v49
	v_fma_f32 v46, v62, v46, v62
	v_fma_f32 v47, v63, v47, v63
	v_fma_f32 v48, v64, v48, v64
	v_fma_f32 v49, v65, v49, v65
	v_mul_f32_e32 v46, 0x3f4c422a, v46
	v_mul_f32_e32 v47, 0x3f4c422a, v47
	v_mul_f32_e32 v48, 0x3f4c422a, v48
	v_mul_f32_e32 v49, 0x3f4c422a, v49
	v_mul_f32_e32 v46, -2.0, v46
	v_mul_f32_e32 v47, -2.0, v47
	v_mul_f32_e32 v48, -2.0, v48
	v_mul_f32_e32 v49, -2.0, v49
	v_mul_f32_e32 v46, 0x3fb8aa3b, v46
	v_mul_f32_e32 v47, 0x3fb8aa3b, v47
	v_mul_f32_e32 v48, 0x3fb8aa3b, v48
	v_mul_f32_e32 v49, 0x3fb8aa3b, v49
	v_exp_f32_e32 v46, v46
	v_exp_f32_e32 v47, v47
	v_exp_f32_e32 v48, v48
	v_exp_f32_e32 v49, v49
	v_add_f32_e32 v46, 1.0, v46
	v_add_f32_e32 v47, 1.0, v47
	v_add_f32_e32 v48, 1.0, v48
	v_add_f32_e32 v49, 1.0, v49
	v_rcp_f32_e32 v46, v46
	v_rcp_f32_e32 v47, v47
	v_rcp_f32_e32 v48, v48
	v_rcp_f32_e32 v49, v49
	v_pk_mul_f32 v[62:63], v[62:63], v[46:47]
	v_pk_mul_f32 v[64:65], v[64:65], v[48:49]
; DEVI float gelu_f(float x) {
;   float u = 0.7978845608028654f * (x + 0.044715f * x * x * x);
;   return x * __builtin_amdgcn_rcpf(1.f + __expf(-2.f * u));
; }
; DEVI void store_bf4(bfu* p, f32x4 v) {
;   uint2 u; u.x = pack2(v[0], v[1]); u.y = pack2(v[2], v[3]);
;   *(uint2*)p = u;
; }
; DEVI void phase2(const Params& p, int l, char* lds) {
;     ...
; #pragma unroll
;     for (int ni = 0; ni < 4; ++ni)
; #pragma unroll
;       for (int mi = 0; mi < 8; ++mi) {
;         f32x4 v = acc[ni][mi];
;         if (do_gelu) { v[0] = gelu_f(v[0]); v[1] = gelu_f(v[1]); v[2] = gelu_f(v[2]); v[3] = gelu_f(v[3]); }
;         int n = n0 + wn * 64 + ni * 16 + fq * 4;
;         int m = m0 + wm * 128 + mi * 16 + fr;
;         store_bf4(proj + (long)m * LDP + n, v);
;       }
.LBB0_733:
	v_cvt_pk_bf16_f32 v208, v62, v63
	v_cvt_pk_bf16_f32 v209, v64, v65
	s_mov_b64 s[36:37], -1
	s_and_b64 vcc, exec, s[0:1]
	s_cbranch_vccz .LBB0_735
	v_cvt_pk_bf16_f32 v212, v54, v55
	v_cvt_pk_bf16_f32 v213, v56, v57
	s_mov_b64 s[36:37], 0
.LBB0_735:
	s_andn2_b64 vcc, exec, s[36:37]
	s_cbranch_vccnz .LBB0_737
	v_mul_f32_e32 v46, 0x3d372713, v54
	v_mul_f32_e32 v47, 0x3d372713, v55
	v_mul_f32_e32 v48, 0x3d372713, v56
	v_mul_f32_e32 v49, 0x3d372713, v57
	v_mul_f32_e32 v46, v54, v46
	v_mul_f32_e32 v47, v55, v47
	v_mul_f32_e32 v48, v56, v48
	v_mul_f32_e32 v49, v57, v49
	v_fma_f32 v46, v54, v46, v54
	v_fma_f32 v47, v55, v47, v55
	v_fma_f32 v48, v56, v48, v56
	v_fma_f32 v49, v57, v49, v57
	v_mul_f32_e32 v46, 0x3f4c422a, v46
	v_mul_f32_e32 v47, 0x3f4c422a, v47
	v_mul_f32_e32 v48, 0x3f4c422a, v48
	v_mul_f32_e32 v49, 0x3f4c422a, v49
	v_mul_f32_e32 v46, -2.0, v46
	v_mul_f32_e32 v47, -2.0, v47
	v_mul_f32_e32 v48, -2.0, v48
	v_mul_f32_e32 v49, -2.0, v49
	v_mul_f32_e32 v46, 0x3fb8aa3b, v46
	v_mul_f32_e32 v47, 0x3fb8aa3b, v47
	v_mul_f32_e32 v48, 0x3fb8aa3b, v48
	v_mul_f32_e32 v49, 0x3fb8aa3b, v49
	v_exp_f32_e32 v46, v46
	v_exp_f32_e32 v47, v47
	v_exp_f32_e32 v48, v48
	v_exp_f32_e32 v49, v49
	v_add_f32_e32 v46, 1.0, v46
	v_add_f32_e32 v47, 1.0, v47
	v_add_f32_e32 v48, 1.0, v48
	v_add_f32_e32 v49, 1.0, v49
	v_rcp_f32_e32 v46, v46
	v_rcp_f32_e32 v47, v47
	v_rcp_f32_e32 v48, v48
	v_rcp_f32_e32 v49, v49
	v_pk_mul_f32 v[46:47], v[54:55], v[46:47]
	s_nop 0
	v_cvt_pk_bf16_f32 v212, v46, v47
	v_pk_mul_f32 v[48:49], v[56:57], v[48:49]
	s_nop 0
	v_cvt_pk_bf16_f32 v213, v48, v49
	v_mul_f32_e32 v46, 0x3d372713, v50
	v_mul_f32_e32 v47, 0x3d372713, v51
	v_mul_f32_e32 v48, 0x3d372713, v52
	v_mul_f32_e32 v49, 0x3d372713, v53
	v_mul_f32_e32 v46, v50, v46
	v_mul_f32_e32 v47, v51, v47
	v_mul_f32_e32 v48, v52, v48
	v_mul_f32_e32 v49, v53, v49
	v_fma_f32 v46, v50, v46, v50
	v_fma_f32 v47, v51, v47, v51
	v_fma_f32 v48, v52, v48, v52
	v_fma_f32 v49, v53, v49, v53
	v_mul_f32_e32 v46, 0x3f4c422a, v46
	v_mul_f32_e32 v47, 0x3f4c422a, v47
	v_mul_f32_e32 v48, 0x3f4c422a, v48
	v_mul_f32_e32 v49, 0x3f4c422a, v49
	v_mul_f32_e32 v46, -2.0, v46
	v_mul_f32_e32 v47, -2.0, v47
	v_mul_f32_e32 v48, -2.0, v48
	v_mul_f32_e32 v49, -2.0, v49
	v_mul_f32_e32 v46, 0x3fb8aa3b, v46
	v_mul_f32_e32 v47, 0x3fb8aa3b, v47
	v_mul_f32_e32 v48, 0x3fb8aa3b, v48
	v_mul_f32_e32 v49, 0x3fb8aa3b, v49
	v_exp_f32_e32 v46, v46
	v_exp_f32_e32 v47, v47
	v_exp_f32_e32 v48, v48
	v_exp_f32_e32 v49, v49
	v_add_f32_e32 v46, 1.0, v46
	v_add_f32_e32 v47, 1.0, v47
	v_add_f32_e32 v48, 1.0, v48
	v_add_f32_e32 v49, 1.0, v49
	v_rcp_f32_e32 v46, v46
	v_rcp_f32_e32 v47, v47
	v_rcp_f32_e32 v48, v48
	v_rcp_f32_e32 v49, v49
	v_pk_mul_f32 v[50:51], v[50:51], v[46:47]
	v_pk_mul_f32 v[52:53], v[52:53], v[48:49]
.LBB0_737:
	v_cvt_pk_bf16_f32 v216, v50, v51
	v_cvt_pk_bf16_f32 v217, v52, v53
	s_mov_b64 s[36:37], -1
	s_and_b64 vcc, exec, s[0:1]
	s_cbranch_vccz .LBB0_739
	v_cvt_pk_bf16_f32 v234, v22, v23
	v_cvt_pk_bf16_f32 v235, v24, v25
	s_mov_b64 s[36:37], 0
.LBB0_739:
	s_andn2_b64 vcc, exec, s[36:37]
	s_cbranch_vccnz .LBB0_741
	v_mul_f32_e32 v46, 0x3d372713, v22
	v_mul_f32_e32 v47, 0x3d372713, v23
	v_mul_f32_e32 v46, v22, v46
	v_mul_f32_e32 v47, v23, v47
	v_fma_f32 v46, v22, v46, v22
	v_fma_f32 v47, v23, v47, v23
	v_mul_f32_e32 v46, 0x3f4c422a, v46
	v_mul_f32_e32 v47, 0x3f4c422a, v47
	v_mul_f32_e32 v46, -2.0, v46
	v_mul_f32_e32 v47, -2.0, v47
	v_mul_f32_e32 v46, 0x3fb8aa3b, v46
	v_mul_f32_e32 v47, 0x3fb8aa3b, v47
	v_exp_f32_e32 v46, v46
	v_exp_f32_e32 v47, v47
	v_add_f32_e32 v46, 1.0, v46
	v_add_f32_e32 v47, 1.0, v47
	v_rcp_f32_e32 v46, v46
	v_rcp_f32_e32 v47, v47
	s_nop 0
	v_pk_mul_f32 v[22:23], v[22:23], v[46:47]
	v_mul_f32_e32 v46, 0x3d372713, v24
	v_mul_f32_e32 v47, 0x3d372713, v25
	v_mul_f32_e32 v46, v24, v46
	v_mul_f32_e32 v47, v25, v47
	v_fma_f32 v46, v24, v46, v24
	v_fma_f32 v47, v25, v47, v25
	v_mul_f32_e32 v46, 0x3f4c422a, v46
	v_mul_f32_e32 v47, 0x3f4c422a, v47
	v_mul_f32_e32 v46, -2.0, v46
	v_mul_f32_e32 v47, -2.0, v47
	v_mul_f32_e32 v46, 0x3fb8aa3b, v46
	v_mul_f32_e32 v47, 0x3fb8aa3b, v47
	v_exp_f32_e32 v46, v46
	v_exp_f32_e32 v47, v47
	v_cvt_pk_bf16_f32 v234, v22, v23
	v_add_f32_e32 v46, 1.0, v46
	v_add_f32_e32 v47, 1.0, v47
	v_rcp_f32_e32 v46, v46
	v_rcp_f32_e32 v47, v47
	s_nop 0
	v_pk_mul_f32 v[24:25], v[24:25], v[46:47]
	s_nop 0
	v_cvt_pk_bf16_f32 v235, v24, v25
	v_mul_f32_e32 v22, 0x3d372713, v16
	v_mul_f32_e32 v23, 0x3d372713, v17
	v_mul_f32_e32 v24, 0x3d372713, v14
	v_mul_f32_e32 v25, 0x3d372713, v15
	v_mul_f32_e32 v22, v16, v22
	v_mul_f32_e32 v23, v17, v23
	v_mul_f32_e32 v24, v14, v24
	v_mul_f32_e32 v25, v15, v25
	v_fma_f32 v22, v16, v22, v16
	v_fma_f32 v23, v17, v23, v17
	v_fma_f32 v24, v14, v24, v14
	v_fma_f32 v25, v15, v25, v15
	v_mul_f32_e32 v22, 0x3f4c422a, v22
	v_mul_f32_e32 v23, 0x3f4c422a, v23
	v_mul_f32_e32 v24, 0x3f4c422a, v24
	v_mul_f32_e32 v25, 0x3f4c422a, v25
	v_mul_f32_e32 v22, -2.0, v22
	v_mul_f32_e32 v23, -2.0, v23
	v_mul_f32_e32 v24, -2.0, v24
	v_mul_f32_e32 v25, -2.0, v25
	v_mul_f32_e32 v22, 0x3fb8aa3b, v22
	v_mul_f32_e32 v23, 0x3fb8aa3b, v23
	v_mul_f32_e32 v24, 0x3fb8aa3b, v24
	v_mul_f32_e32 v25, 0x3fb8aa3b, v25
	v_exp_f32_e32 v22, v22
	v_exp_f32_e32 v23, v23
	v_exp_f32_e32 v24, v24
	v_exp_f32_e32 v25, v25
	v_add_f32_e32 v22, 1.0, v22
	v_add_f32_e32 v23, 1.0, v23
	v_add_f32_e32 v24, 1.0, v24
	v_add_f32_e32 v25, 1.0, v25
	v_rcp_f32_e32 v22, v22
	v_rcp_f32_e32 v23, v23
	v_rcp_f32_e32 v24, v24
	v_rcp_f32_e32 v25, v25
	v_pk_mul_f32 v[16:17], v[16:17], v[22:23]
	v_pk_mul_f32 v[14:15], v[14:15], v[24:25]
; DEVI float gelu_f(float x) {
;   float u = 0.7978845608028654f * (x + 0.044715f * x * x * x);
;   return x * __builtin_amdgcn_rcpf(1.f + __expf(-2.f * u));
; }
; DEVI void store_bf4(bfu* p, f32x4 v) {
;   uint2 u; u.x = pack2(v[0], v[1]); u.y = pack2(v[2], v[3]);
;   *(uint2*)p = u;
; }
; DEVI void phase2(const Params& p, int l, char* lds) {
;     ...
; #pragma unroll
;     for (int ni = 0; ni < 4; ++ni)
; #pragma unroll
;       for (int mi = 0; mi < 8; ++mi) {
;         f32x4 v = acc[ni][mi];
;         if (do_gelu) { v[0] = gelu_f(v[0]); v[1] = gelu_f(v[1]); v[2] = gelu_f(v[2]); v[3] = gelu_f(v[3]); }
;         int n = n0 + wn * 64 + ni * 16 + fq * 4;
;         int m = m0 + wm * 128 + mi * 16 + fr;
;         store_bf4(proj + (long)m * LDP + n, v);
;       }
.LBB0_741:
	v_cvt_pk_bf16_f32 v238, v16, v17
	v_cvt_pk_bf16_f32 v239, v14, v15
	s_mov_b64 s[36:37], -1
	s_and_b64 vcc, exec, s[0:1]
	s_cbranch_vccz .LBB0_743
	v_cvt_pk_bf16_f32 v198, v42, v43
	v_cvt_pk_bf16_f32 v199, v44, v45
	s_nop 1
	v_permlane16_swap_b32_e32 v196, v198
	v_permlane16_swap_b32_e32 v197, v199
	s_nop 1
	global_store_dwordx4 v[132:133], v[196:199], off offset:64
	s_mov_b64 s[36:37], 0
.LBB0_743:
	s_andn2_b64 vcc, exec, s[36:37]
	s_cbranch_vccnz .LBB0_745
	v_mul_f32_e32 v14, 0x3d372713, v42
	v_mul_f32_e32 v15, 0x3d372713, v43
	v_mul_f32_e32 v16, 0x3d372713, v44
	v_mul_f32_e32 v17, 0x3d372713, v45
	v_mul_f32_e32 v14, v42, v14
	v_mul_f32_e32 v15, v43, v15
	v_mul_f32_e32 v16, v44, v16
	v_mul_f32_e32 v17, v45, v17
	v_fma_f32 v14, v42, v14, v42
	v_fma_f32 v15, v43, v15, v43
	v_fma_f32 v16, v44, v16, v44
	v_fma_f32 v17, v45, v17, v45
	v_mul_f32_e32 v14, 0x3f4c422a, v14
	v_mul_f32_e32 v15, 0x3f4c422a, v15
	v_mul_f32_e32 v16, 0x3f4c422a, v16
	v_mul_f32_e32 v17, 0x3f4c422a, v17
	v_mul_f32_e32 v14, -2.0, v14
	v_mul_f32_e32 v15, -2.0, v15
	v_mul_f32_e32 v16, -2.0, v16
	v_mul_f32_e32 v17, -2.0, v17
	v_mul_f32_e32 v14, 0x3fb8aa3b, v14
	v_mul_f32_e32 v15, 0x3fb8aa3b, v15
	v_mul_f32_e32 v16, 0x3fb8aa3b, v16
	v_mul_f32_e32 v17, 0x3fb8aa3b, v17
	v_exp_f32_e32 v14, v14
	v_exp_f32_e32 v15, v15
	v_exp_f32_e32 v16, v16
	v_exp_f32_e32 v17, v17
	v_add_f32_e32 v14, 1.0, v14
	v_add_f32_e32 v15, 1.0, v15
	v_add_f32_e32 v16, 1.0, v16
	v_add_f32_e32 v17, 1.0, v17
	v_rcp_f32_e32 v14, v14
	v_rcp_f32_e32 v15, v15
	v_rcp_f32_e32 v16, v16
	v_rcp_f32_e32 v17, v17
	v_pk_mul_f32 v[14:15], v[42:43], v[14:15]
	s_nop 0
	v_cvt_pk_bf16_f32 v198, v14, v15
	v_pk_mul_f32 v[16:17], v[44:45], v[16:17]
	s_nop 0
	v_cvt_pk_bf16_f32 v199, v16, v17
	s_nop 1
	v_permlane16_swap_b32_e32 v196, v198
	v_permlane16_swap_b32_e32 v197, v199
	s_nop 1
	global_store_dwordx4 v[132:133], v[196:199], off offset:64
	v_mul_f32_e32 v14, 0x3d372713, v38
	v_mul_f32_e32 v15, 0x3d372713, v39
	v_mul_f32_e32 v16, 0x3d372713, v40
	v_mul_f32_e32 v17, 0x3d372713, v41
	v_mul_f32_e32 v14, v38, v14
	v_mul_f32_e32 v15, v39, v15
	v_mul_f32_e32 v16, v40, v16
	v_mul_f32_e32 v17, v41, v17
	v_fma_f32 v14, v38, v14, v38
	v_fma_f32 v15, v39, v15, v39
	v_fma_f32 v16, v40, v16, v40
	v_fma_f32 v17, v41, v17, v41
	v_mul_f32_e32 v14, 0x3f4c422a, v14
	v_mul_f32_e32 v15, 0x3f4c422a, v15
	v_mul_f32_e32 v16, 0x3f4c422a, v16
	v_mul_f32_e32 v17, 0x3f4c422a, v17
	v_mul_f32_e32 v14, -2.0, v14
	v_mul_f32_e32 v15, -2.0, v15
	v_mul_f32_e32 v16, -2.0, v16
	v_mul_f32_e32 v17, -2.0, v17
	v_mul_f32_e32 v14, 0x3fb8aa3b, v14
	v_mul_f32_e32 v15, 0x3fb8aa3b, v15
	v_mul_f32_e32 v16, 0x3fb8aa3b, v16
	v_mul_f32_e32 v17, 0x3fb8aa3b, v17
	v_exp_f32_e32 v14, v14
	v_exp_f32_e32 v15, v15
	v_exp_f32_e32 v16, v16
	v_exp_f32_e32 v17, v17
	v_add_f32_e32 v14, 1.0, v14
	v_add_f32_e32 v15, 1.0, v15
	v_add_f32_e32 v16, 1.0, v16
	v_add_f32_e32 v17, 1.0, v17
	v_rcp_f32_e32 v14, v14
	v_rcp_f32_e32 v15, v15
	v_rcp_f32_e32 v16, v16
	v_rcp_f32_e32 v17, v17
	v_pk_mul_f32 v[38:39], v[38:39], v[14:15]
	v_pk_mul_f32 v[40:41], v[40:41], v[16:17]
.LBB0_745:
	v_cvt_pk_bf16_f32 v202, v38, v39
	v_cvt_pk_bf16_f32 v203, v40, v41
	s_mov_b64 s[36:37], -1
	s_and_b64 vcc, exec, s[0:1]
	s_nop 1
	v_permlane16_swap_b32_e32 v200, v202
	v_permlane16_swap_b32_e32 v201, v203
	s_nop 1
	global_store_dwordx4 v[130:131], v[200:203], off offset:64
	s_cbranch_vccz .LBB0_747
	v_cvt_pk_bf16_f32 v206, v34, v35
	v_cvt_pk_bf16_f32 v207, v36, v37
	s_nop 1
	v_permlane16_swap_b32_e32 v204, v206
	v_permlane16_swap_b32_e32 v205, v207
	s_nop 1
	global_store_dwordx4 v[126:127], v[204:207], off offset:64
	s_mov_b64 s[36:37], 0
.LBB0_747:
	s_andn2_b64 vcc, exec, s[36:37]
	s_cbranch_vccnz .LBB0_749
	v_mul_f32_e32 v14, 0x3d372713, v34
	v_mul_f32_e32 v15, 0x3d372713, v35
	v_mul_f32_e32 v16, 0x3d372713, v36
	v_mul_f32_e32 v17, 0x3d372713, v37
	v_mul_f32_e32 v14, v34, v14
	v_mul_f32_e32 v15, v35, v15
	v_mul_f32_e32 v16, v36, v16
	v_mul_f32_e32 v17, v37, v17
	v_fma_f32 v14, v34, v14, v34
	v_fma_f32 v15, v35, v15, v35
	v_fma_f32 v16, v36, v16, v36
	v_fma_f32 v17, v37, v17, v37
	v_mul_f32_e32 v14, 0x3f4c422a, v14
	v_mul_f32_e32 v15, 0x3f4c422a, v15
	v_mul_f32_e32 v16, 0x3f4c422a, v16
	v_mul_f32_e32 v17, 0x3f4c422a, v17
	v_mul_f32_e32 v14, -2.0, v14
	v_mul_f32_e32 v15, -2.0, v15
	v_mul_f32_e32 v16, -2.0, v16
	v_mul_f32_e32 v17, -2.0, v17
	v_mul_f32_e32 v14, 0x3fb8aa3b, v14
	v_mul_f32_e32 v15, 0x3fb8aa3b, v15
	v_mul_f32_e32 v16, 0x3fb8aa3b, v16
	v_mul_f32_e32 v17, 0x3fb8aa3b, v17
	v_exp_f32_e32 v14, v14
	v_exp_f32_e32 v15, v15
	v_exp_f32_e32 v16, v16
	v_exp_f32_e32 v17, v17
	v_add_f32_e32 v14, 1.0, v14
	v_add_f32_e32 v15, 1.0, v15
	v_add_f32_e32 v16, 1.0, v16
	v_add_f32_e32 v17, 1.0, v17
	v_rcp_f32_e32 v14, v14
	v_rcp_f32_e32 v15, v15
	v_rcp_f32_e32 v16, v16
	v_rcp_f32_e32 v17, v17
	v_pk_mul_f32 v[14:15], v[34:35], v[14:15]
	s_nop 0
	v_cvt_pk_bf16_f32 v206, v14, v15
	v_pk_mul_f32 v[16:17], v[36:37], v[16:17]
	s_nop 0
	v_cvt_pk_bf16_f32 v207, v16, v17
	s_nop 1
	v_permlane16_swap_b32_e32 v204, v206
	v_permlane16_swap_b32_e32 v205, v207
	s_nop 1
	global_store_dwordx4 v[126:127], v[204:207], off offset:64
	v_mul_f32_e32 v14, 0x3d372713, v30
	v_mul_f32_e32 v15, 0x3d372713, v31
	v_mul_f32_e32 v16, 0x3d372713, v32
	v_mul_f32_e32 v17, 0x3d372713, v33
	v_mul_f32_e32 v14, v30, v14
	v_mul_f32_e32 v15, v31, v15
	v_mul_f32_e32 v16, v32, v16
	v_mul_f32_e32 v17, v33, v17
	v_fma_f32 v14, v30, v14, v30
	v_fma_f32 v15, v31, v15, v31
	v_fma_f32 v16, v32, v16, v32
	v_fma_f32 v17, v33, v17, v33
	v_mul_f32_e32 v14, 0x3f4c422a, v14
	v_mul_f32_e32 v15, 0x3f4c422a, v15
	v_mul_f32_e32 v16, 0x3f4c422a, v16
	v_mul_f32_e32 v17, 0x3f4c422a, v17
	v_mul_f32_e32 v14, -2.0, v14
	v_mul_f32_e32 v15, -2.0, v15
	v_mul_f32_e32 v16, -2.0, v16
	v_mul_f32_e32 v17, -2.0, v17
	v_mul_f32_e32 v14, 0x3fb8aa3b, v14
	v_mul_f32_e32 v15, 0x3fb8aa3b, v15
	v_mul_f32_e32 v16, 0x3fb8aa3b, v16
	v_mul_f32_e32 v17, 0x3fb8aa3b, v17
	v_exp_f32_e32 v14, v14
	v_exp_f32_e32 v15, v15
	v_exp_f32_e32 v16, v16
	v_exp_f32_e32 v17, v17
	v_add_f32_e32 v14, 1.0, v14
	v_add_f32_e32 v15, 1.0, v15
	v_add_f32_e32 v16, 1.0, v16
	v_add_f32_e32 v17, 1.0, v17
	v_rcp_f32_e32 v14, v14
	v_rcp_f32_e32 v15, v15
	v_rcp_f32_e32 v16, v16
	v_rcp_f32_e32 v17, v17
	v_pk_mul_f32 v[30:31], v[30:31], v[14:15]
	v_pk_mul_f32 v[32:33], v[32:33], v[16:17]
; DEVI float gelu_f(float x) {
;   float u = 0.7978845608028654f * (x + 0.044715f * x * x * x);
;   return x * __builtin_amdgcn_rcpf(1.f + __expf(-2.f * u));
; }
; DEVI void store_bf4(bfu* p, f32x4 v) {
;   uint2 u; u.x = pack2(v[0], v[1]); u.y = pack2(v[2], v[3]);
;   *(uint2*)p = u;
; }
; DEVI void phase2(const Params& p, int l, char* lds) {
;     ...
; #pragma unroll
;     for (int ni = 0; ni < 4; ++ni)
; #pragma unroll
;       for (int mi = 0; mi < 8; ++mi) {
;         f32x4 v = acc[ni][mi];
;         if (do_gelu) { v[0] = gelu_f(v[0]); v[1] = gelu_f(v[1]); v[2] = gelu_f(v[2]); v[3] = gelu_f(v[3]); }
;         int n = n0 + wn * 64 + ni * 16 + fq * 4;
;         int m = m0 + wm * 128 + mi * 16 + fr;
;         store_bf4(proj + (long)m * LDP + n, v);
;       }
.LBB0_749:
	v_cvt_pk_bf16_f32 v210, v30, v31
	v_cvt_pk_bf16_f32 v211, v32, v33
	s_mov_b64 s[36:37], -1
	s_and_b64 vcc, exec, s[0:1]
	s_nop 1
	v_permlane16_swap_b32_e32 v208, v210
	v_permlane16_swap_b32_e32 v209, v211
	s_nop 1
	global_store_dwordx4 v[122:123], v[208:211], off offset:64
	s_cbranch_vccz .LBB0_751
	v_cvt_pk_bf16_f32 v214, v26, v27
	v_cvt_pk_bf16_f32 v215, v28, v29
	s_nop 1
	v_permlane16_swap_b32_e32 v212, v214
	v_permlane16_swap_b32_e32 v213, v215
	s_nop 1
	global_store_dwordx4 v[118:119], v[212:215], off offset:64
	s_mov_b64 s[36:37], 0
.LBB0_751:
	s_andn2_b64 vcc, exec, s[36:37]
	s_cbranch_vccnz .LBB0_753
	v_mul_f32_e32 v14, 0x3d372713, v26
	v_mul_f32_e32 v15, 0x3d372713, v27
	v_mul_f32_e32 v16, 0x3d372713, v28
	v_mul_f32_e32 v17, 0x3d372713, v29
	v_mul_f32_e32 v14, v26, v14
	v_mul_f32_e32 v15, v27, v15
	v_mul_f32_e32 v16, v28, v16
	v_mul_f32_e32 v17, v29, v17
	v_fma_f32 v14, v26, v14, v26
	v_fma_f32 v15, v27, v15, v27
	v_fma_f32 v16, v28, v16, v28
	v_fma_f32 v17, v29, v17, v29
	v_mul_f32_e32 v14, 0x3f4c422a, v14
	v_mul_f32_e32 v15, 0x3f4c422a, v15
	v_mul_f32_e32 v16, 0x3f4c422a, v16
	v_mul_f32_e32 v17, 0x3f4c422a, v17
	v_mul_f32_e32 v14, -2.0, v14
	v_mul_f32_e32 v15, -2.0, v15
	v_mul_f32_e32 v16, -2.0, v16
	v_mul_f32_e32 v17, -2.0, v17
	v_mul_f32_e32 v14, 0x3fb8aa3b, v14
	v_mul_f32_e32 v15, 0x3fb8aa3b, v15
	v_mul_f32_e32 v16, 0x3fb8aa3b, v16
	v_mul_f32_e32 v17, 0x3fb8aa3b, v17
	v_exp_f32_e32 v14, v14
	v_exp_f32_e32 v15, v15
	v_exp_f32_e32 v16, v16
	v_exp_f32_e32 v17, v17
	v_add_f32_e32 v14, 1.0, v14
	v_add_f32_e32 v15, 1.0, v15
	v_add_f32_e32 v16, 1.0, v16
	v_add_f32_e32 v17, 1.0, v17
	v_rcp_f32_e32 v14, v14
	v_rcp_f32_e32 v15, v15
	v_rcp_f32_e32 v16, v16
	v_rcp_f32_e32 v17, v17
	v_pk_mul_f32 v[14:15], v[26:27], v[14:15]
	s_nop 0
	v_cvt_pk_bf16_f32 v214, v14, v15
	v_pk_mul_f32 v[16:17], v[28:29], v[16:17]
	s_nop 0
	v_cvt_pk_bf16_f32 v215, v16, v17
	s_nop 1
	v_permlane16_swap_b32_e32 v212, v214
	v_permlane16_swap_b32_e32 v213, v215
	s_nop 1
	global_store_dwordx4 v[118:119], v[212:215], off offset:64
	v_mul_f32_e32 v14, 0x3d372713, v18
	v_mul_f32_e32 v15, 0x3d372713, v19
	v_mul_f32_e32 v16, 0x3d372713, v20
	v_mul_f32_e32 v17, 0x3d372713, v21
	v_mul_f32_e32 v14, v18, v14
	v_mul_f32_e32 v15, v19, v15
	v_mul_f32_e32 v16, v20, v16
	v_mul_f32_e32 v17, v21, v17
	v_fma_f32 v14, v18, v14, v18
	v_fma_f32 v15, v19, v15, v19
	v_fma_f32 v16, v20, v16, v20
	v_fma_f32 v17, v21, v17, v21
	v_mul_f32_e32 v14, 0x3f4c422a, v14
	v_mul_f32_e32 v15, 0x3f4c422a, v15
	v_mul_f32_e32 v16, 0x3f4c422a, v16
	v_mul_f32_e32 v17, 0x3f4c422a, v17
	v_mul_f32_e32 v14, -2.0, v14
	v_mul_f32_e32 v15, -2.0, v15
	v_mul_f32_e32 v16, -2.0, v16
	v_mul_f32_e32 v17, -2.0, v17
	v_mul_f32_e32 v14, 0x3fb8aa3b, v14
	v_mul_f32_e32 v15, 0x3fb8aa3b, v15
	v_mul_f32_e32 v16, 0x3fb8aa3b, v16
	v_mul_f32_e32 v17, 0x3fb8aa3b, v17
	v_exp_f32_e32 v14, v14
	v_exp_f32_e32 v15, v15
	v_exp_f32_e32 v16, v16
	v_exp_f32_e32 v17, v17
	v_add_f32_e32 v14, 1.0, v14
	v_add_f32_e32 v15, 1.0, v15
	v_add_f32_e32 v16, 1.0, v16
	v_add_f32_e32 v17, 1.0, v17
	v_rcp_f32_e32 v14, v14
	v_rcp_f32_e32 v15, v15
	v_rcp_f32_e32 v16, v16
	v_rcp_f32_e32 v17, v17
	v_pk_mul_f32 v[18:19], v[18:19], v[14:15]
	v_pk_mul_f32 v[20:21], v[20:21], v[16:17]
.LBB0_753:
	v_cvt_pk_bf16_f32 v218, v18, v19
	v_cvt_pk_bf16_f32 v219, v20, v21
	s_mov_b64 s[36:37], -1
	s_and_b64 vcc, exec, s[0:1]
	s_nop 1
	v_permlane16_swap_b32_e32 v216, v218
	v_permlane16_swap_b32_e32 v217, v219
	s_nop 1
	global_store_dwordx4 v[112:113], v[216:219], off offset:64
	s_cbranch_vccz .LBB0_755
	v_cvt_pk_bf16_f32 v236, v10, v11
	v_cvt_pk_bf16_f32 v237, v12, v13
	s_nop 1
	v_permlane16_swap_b32_e32 v234, v236
	v_permlane16_swap_b32_e32 v235, v237
	s_nop 1
	global_store_dwordx4 v[4:5], v[234:237], off offset:64
	s_mov_b64 s[36:37], 0
.LBB0_755:
	s_andn2_b64 vcc, exec, s[36:37]
	s_cbranch_vccnz .LBB0_675
	v_mul_f32_e32 v14, 0x3d372713, v10
	v_mul_f32_e32 v15, 0x3d372713, v11
	v_mul_f32_e32 v14, v10, v14
	v_mul_f32_e32 v15, v11, v15
	v_fma_f32 v14, v10, v14, v10
	v_fma_f32 v15, v11, v15, v11
	v_mul_f32_e32 v14, 0x3f4c422a, v14
	v_mul_f32_e32 v15, 0x3f4c422a, v15
	v_mul_f32_e32 v14, -2.0, v14
	v_mul_f32_e32 v15, -2.0, v15
	v_mul_f32_e32 v14, 0x3fb8aa3b, v14
	v_mul_f32_e32 v15, 0x3fb8aa3b, v15
	v_exp_f32_e32 v14, v14
	v_exp_f32_e32 v15, v15
	v_add_f32_e32 v14, 1.0, v14
	v_add_f32_e32 v15, 1.0, v15
	v_rcp_f32_e32 v14, v14
	v_rcp_f32_e32 v15, v15
	s_nop 0
	v_pk_mul_f32 v[10:11], v[10:11], v[14:15]
	v_mul_f32_e32 v14, 0x3d372713, v12
	v_mul_f32_e32 v15, 0x3d372713, v13
	v_mul_f32_e32 v14, v12, v14
	v_mul_f32_e32 v15, v13, v15
	v_fma_f32 v14, v12, v14, v12
	v_fma_f32 v15, v13, v15, v13
	v_mul_f32_e32 v14, 0x3f4c422a, v14
	v_mul_f32_e32 v15, 0x3f4c422a, v15
	v_mul_f32_e32 v14, -2.0, v14
	v_mul_f32_e32 v15, -2.0, v15
	v_mul_f32_e32 v14, 0x3fb8aa3b, v14
	v_mul_f32_e32 v15, 0x3fb8aa3b, v15
	v_exp_f32_e32 v14, v14
	v_exp_f32_e32 v15, v15
	v_cvt_pk_bf16_f32 v236, v10, v11
	v_add_f32_e32 v14, 1.0, v14
	v_add_f32_e32 v15, 1.0, v15
	v_rcp_f32_e32 v14, v14
	v_rcp_f32_e32 v15, v15
	s_nop 0
	v_pk_mul_f32 v[12:13], v[12:13], v[14:15]
	s_nop 0
	v_cvt_pk_bf16_f32 v237, v12, v13
	s_nop 1
	v_permlane16_swap_b32_e32 v234, v236
	v_permlane16_swap_b32_e32 v235, v237
	s_nop 1
	global_store_dwordx4 v[4:5], v[234:237], off offset:64
	v_mul_f32_e32 v4, 0x3d372713, v8
	v_mul_f32_e32 v5, 0x3d372713, v9
	v_mul_f32_e32 v10, 0x3d372713, v6
	v_mul_f32_e32 v11, 0x3d372713, v7
	v_mul_f32_e32 v4, v8, v4
	v_mul_f32_e32 v5, v9, v5
	v_mul_f32_e32 v10, v6, v10
	v_mul_f32_e32 v11, v7, v11
	v_fma_f32 v4, v8, v4, v8
	v_fma_f32 v5, v9, v5, v9
	v_fma_f32 v10, v6, v10, v6
	v_fma_f32 v11, v7, v11, v7
	v_mul_f32_e32 v4, 0x3f4c422a, v4
	v_mul_f32_e32 v5, 0x3f4c422a, v5
	v_mul_f32_e32 v10, 0x3f4c422a, v10
	v_mul_f32_e32 v11, 0x3f4c422a, v11
	v_mul_f32_e32 v4, -2.0, v4
	v_mul_f32_e32 v5, -2.0, v5
	v_mul_f32_e32 v10, -2.0, v10
	v_mul_f32_e32 v11, -2.0, v11
	v_mul_f32_e32 v4, 0x3fb8aa3b, v4
	v_mul_f32_e32 v5, 0x3fb8aa3b, v5
	v_mul_f32_e32 v10, 0x3fb8aa3b, v10
	v_mul_f32_e32 v11, 0x3fb8aa3b, v11
	v_exp_f32_e32 v4, v4
	v_exp_f32_e32 v5, v5
	v_exp_f32_e32 v10, v10
	v_exp_f32_e32 v11, v11
	v_add_f32_e32 v4, 1.0, v4
	v_add_f32_e32 v5, 1.0, v5
	v_add_f32_e32 v10, 1.0, v10
	v_add_f32_e32 v11, 1.0, v11
	v_rcp_f32_e32 v4, v4
	v_rcp_f32_e32 v5, v5
	v_rcp_f32_e32 v10, v10
	v_rcp_f32_e32 v11, v11
	v_pk_mul_f32 v[8:9], v[8:9], v[4:5]
	v_pk_mul_f32 v[6:7], v[6:7], v[10:11]
	s_branch .LBB0_675
